# speedup vs baseline: 1.0256x; 1.0043x over previous
; __device__ __forceinline__ float bf2f(u16 h) { return __uint_as_float(((unsigned)h) << 16); }
; __device__ __forceinline__ float siluf_(float x) { return x * __builtin_amdgcn_rcpf(1.0f + __expf(-x)); }
; __device__ __forceinline__ void phase_ain(const Params& P, int l, int bid, int nb) {
;     ...
;   for (int r = bid * 8 + wid; r < P.tg; r += nb * 8) {
;     float ov[16];
;     float ss = 0.f;
; #pragma unroll
;     for (int hh = 0; hh < 2; ++hh) {
;       u16x8 a = *(const u16x8*)(P.of + (long)r * D + c0 + hh * 8);
;       u16x8 a2 = *(const u16x8*)(P.h + (long)r * HS + c0 + hh * 8);
;       u16x8 b2 = *(const u16x8*)(P.h + (long)r * HS + 1024 + c0 + hh * 8);
; #pragma unroll
;       for (int e = 0; e < 8; ++e) { float v = bf2f(a[e]) + (bf2f(a2[e]) + bf2f(b2[e])); ov[hh * 8 + e] = v; ss += v * v; }
;     }
; #pragma unroll
;     for (int o = 8; o >= 1; o >>= 1) ss += shfl_xor_l(ss, lane, o);
;     float rinv = rsqrtf(ss * (1.0f / 256.0f) + EPS);
; #pragma unroll
;     for (int hh = 0; hh < 2; ++hh) {
;       u16x8 rv = *(const u16x8*)(P.h + (long)r * HS + C_R + c0 + hh * 8);
;       u16x8 o;
; #pragma unroll
;       for (int e = 0; e < 8; ++e) o[e] = f2bf(ov[hh * 8 + e] * rinv * og[c0 + hh * 8 + e] * siluf_(bf2f(rv[e])));
.LBB0_155:
	v_lshl_add_u64 v[30:31], v[20:21], 0, v[0:1]
	v_add_co_u32_e32 v6, vcc, 0x30e00000, v30
	v_lshl_add_u64 v[34:35], v[22:23], 0, v[0:1]
	s_nop 0
	v_addc_co_u32_e32 v7, vcc, 0, v31, vcc
	v_add_co_u32_e32 v8, vcc, 0xe600000, v34
	global_load_dwordx4 v[2:5], v[6:7], off
	s_nop 0
	v_addc_co_u32_e32 v9, vcc, 0, v35, vcc
	global_load_dwordx4 v[26:29], v[8:9], off
	global_load_dwordx4 v[42:45], v[8:9], off offset:2048
	global_load_dwordx4 v[14:17], v[6:7], off offset:16
	global_load_dwordx4 v[10:13], v[8:9], off offset:16
	s_nop 0
	global_load_dwordx4 v[6:9], v[8:9], off offset:2064
	s_mov_b32 s8, 0xe601000
	v_add_co_u32_e32 v58, vcc, s8, v34
	v_add_u32_e32 v36, s62, v36
	s_nop 0
	v_addc_co_u32_e32 v59, vcc, 0, v35, vcc
	v_lshl_add_u64 v[20:21], v[20:21], 0, s[10:11]
	v_lshl_add_u64 v[22:23], v[22:23], 0, s[14:15]
	global_load_dwordx4 v[196:199], v[58:59], off
	global_load_dwordx4 v[200:203], v[18:19], off offset:16
	global_load_dwordx4 v[204:207], v[18:19], off
	global_load_dwordx4 v[208:211], v[58:59], off offset:16
	global_load_dwordx4 v[212:215], v[18:19], off offset:48
	global_load_dwordx4 v[216:219], v[18:19], off offset:32
	s_waitcnt vmcnt(0) lgkmcnt(0)
	v_and_b32_e32 v51, 0xffff0000, v26
	v_and_b32_e32 v35, 0xffff0000, v2
	v_lshlrev_b32_e32 v34, 16, v2
	v_and_b32_e32 v33, 0xffff0000, v13
	v_lshlrev_b32_e32 v32, 16, v13
	v_and_b32_e32 v47, 0xffff0000, v9
	v_lshlrev_b32_e32 v46, 16, v9
	v_pk_add_f32 v[32:33], v[32:33], v[46:47]
	v_mov_b64_e32 v[46:47], v[196:197]
	v_mov_b64_e32 v[48:49], v[198:199]
	v_lshlrev_b32_e32 v50, 16, v26
	v_lshlrev_b32_e32 v26, 16, v43
	v_and_b32_e32 v53, 0xffff0000, v42
	v_lshlrev_b32_e32 v52, 16, v42
	v_and_b32_e32 v67, 0xffff0000, v44
	v_lshlrev_b32_e32 v66, 16, v44
	v_pk_add_f32 v[50:51], v[50:51], v[52:53]
	v_and_b32_e32 v13, 0xffff0000, v12
	v_pk_add_f32 v[34:35], v[50:51], v[34:35]
	v_mov_b64_e32 v[50:51], v[200:201]
	v_mov_b64_e32 v[52:53], v[202:203]
	v_mov_b64_e32 v[54:55], v[204:205]
	v_mov_b64_e32 v[56:57], v[206:207]
	v_lshlrev_b32_e32 v12, 16, v12
	v_pk_mul_f32 v[60:61], v[34:35], v[34:35]
	v_and_b32_e32 v25, 0xffff0000, v17
	v_lshlrev_b32_e32 v24, 16, v17
	v_pk_add_f32 v[24:25], v[32:33], v[24:25]
	s_waitcnt vmcnt(0) lgkmcnt(0)
	v_lshlrev_b32_e32 v62, 16, v46
	v_mul_f32_e32 v2, 0xbfb8aa3b, v62
	v_exp_f32_e32 v2, v2
	v_and_b32_e32 v63, 0xffff0000, v46
	v_pk_mul_f32 v[32:33], v[24:25], v[24:25]
	v_add_f32_e32 v2, 1.0, v2
	v_rcp_f32_e32 v64, v2
	v_mul_f32_e32 v2, 0xbfb8aa3b, v63
	v_exp_f32_e32 v2, v2
	s_nop 0
	v_add_f32_e32 v2, 1.0, v2
	v_rcp_f32_e32 v65, v2
	v_lshlrev_b32_e32 v2, 16, v27
	v_pk_mul_f32 v[62:63], v[64:65], v[62:63]
	v_and_b32_e32 v65, 0xffff0000, v3
	v_lshlrev_b32_e32 v64, 16, v3
	v_and_b32_e32 v3, 0xffff0000, v27
	v_and_b32_e32 v27, 0xffff0000, v43
	v_pk_add_f32 v[2:3], v[2:3], v[26:27]
	s_nop 0
	v_pk_add_f32 v[42:43], v[2:3], v[64:65]
	v_lshlrev_b32_e32 v2, 16, v47
	v_mul_f32_e32 v9, 0xbfb8aa3b, v2
	v_exp_f32_e32 v9, v9
	v_and_b32_e32 v3, 0xffff0000, v47
	v_pk_mul_f32 v[64:65], v[42:43], v[42:43]
	v_add_f32_e32 v9, 1.0, v9
	v_rcp_f32_e32 v26, v9
	v_mul_f32_e32 v9, 0xbfb8aa3b, v3
	v_exp_f32_e32 v9, v9
	s_nop 0
	v_add_f32_e32 v9, 1.0, v9
	v_rcp_f32_e32 v27, v9
	v_and_b32_e32 v9, 0xffff0000, v8
	v_lshlrev_b32_e32 v8, 16, v8
	v_pk_add_f32 v[8:9], v[12:13], v[8:9]
	v_pk_mul_f32 v[46:47], v[26:27], v[2:3]
	v_and_b32_e32 v27, 0xffff0000, v28
	v_lshlrev_b32_e32 v26, 16, v28
	v_and_b32_e32 v3, 0xffff0000, v4
	v_lshlrev_b32_e32 v2, 16, v4
	v_pk_add_f32 v[26:27], v[26:27], v[66:67]
	v_lshlrev_b32_e32 v28, 16, v10
	v_pk_add_f32 v[66:67], v[26:27], v[2:3]
	v_lshlrev_b32_e32 v2, 16, v48
	v_mul_f32_e32 v4, 0xbfb8aa3b, v2
	v_exp_f32_e32 v4, v4
	v_and_b32_e32 v3, 0xffff0000, v48
	v_pk_mul_f32 v[68:69], v[66:67], v[66:67]
	v_add_f32_e32 v4, 1.0, v4
	v_rcp_f32_e32 v26, v4
	v_mul_f32_e32 v4, 0xbfb8aa3b, v3
	v_exp_f32_e32 v4, v4
	s_nop 0
	v_add_f32_e32 v4, 1.0, v4
	v_rcp_f32_e32 v27, v4
	v_lshlrev_b32_e32 v4, 16, v29
	v_pk_mul_f32 v[70:71], v[26:27], v[2:3]
	v_and_b32_e32 v3, 0xffff0000, v5
	v_lshlrev_b32_e32 v2, 16, v5
	v_and_b32_e32 v5, 0xffff0000, v29
	v_and_b32_e32 v27, 0xffff0000, v45
	v_lshlrev_b32_e32 v26, 16, v45
	v_pk_add_f32 v[4:5], v[4:5], v[26:27]
	v_and_b32_e32 v29, 0xffff0000, v10
	v_pk_add_f32 v[44:45], v[4:5], v[2:3]
	v_and_b32_e32 v3, 0xffff0000, v49
	v_lshlrev_b32_e32 v2, 16, v49
	v_mul_f32_e32 v4, 0xbfb8aa3b, v2
	v_mul_f32_e32 v5, 0xbfb8aa3b, v3
	v_exp_f32_e32 v4, v4
	v_exp_f32_e32 v5, v5
	v_and_b32_e32 v27, 0xffff0000, v14
	v_lshlrev_b32_e32 v26, 16, v14
	v_add_f32_e32 v4, 1.0, v4
	v_add_f32_e32 v5, 1.0, v5
	v_rcp_f32_e32 v4, v4
	v_rcp_f32_e32 v5, v5
	v_lshlrev_b32_e32 v14, 16, v11
	v_lshlrev_b32_e32 v10, 16, v7
	v_pk_mul_f32 v[72:73], v[44:45], v[44:45]
	v_pk_mul_f32 v[48:49], v[4:5], v[2:3]
	v_mov_b64_e32 v[2:3], v[208:209]
	v_mov_b64_e32 v[4:5], v[210:211]
	v_and_b32_e32 v59, 0xffff0000, v6
	v_lshlrev_b32_e32 v58, 16, v6
	v_pk_add_f32 v[28:29], v[28:29], v[58:59]
	s_nop 0
	v_pk_add_f32 v[26:27], v[28:29], v[26:27]
	s_waitcnt vmcnt(0) lgkmcnt(0)
; __device__ __forceinline__ float bf2f(u16 h) { return __uint_as_float(((unsigned)h) << 16); }
; __device__ __forceinline__ float siluf_(float x) { return x * __builtin_amdgcn_rcpf(1.0f + __expf(-x)); }
; __device__ __forceinline__ void phase_ain(const Params& P, int l, int bid, int nb) {
;     ...
;       for (int e = 0; e < 8; ++e) { float v = bf2f(a[e]) + (bf2f(a2[e]) + bf2f(b2[e])); ov[hh * 8 + e] = v; ss += v * v; }
;     }
; #pragma unroll
;     for (int o = 8; o >= 1; o >>= 1) ss += shfl_xor_l(ss, lane, o);
;     float rinv = rsqrtf(ss * (1.0f / 256.0f) + EPS);
; #pragma unroll
;     for (int hh = 0; hh < 2; ++hh) {
;       u16x8 rv = *(const u16x8*)(P.h + (long)r * HS + C_R + c0 + hh * 8);
;       u16x8 o;
; #pragma unroll
;       for (int e = 0; e < 8; ++e) o[e] = f2bf(ov[hh * 8 + e] * rinv * og[c0 + hh * 8 + e] * siluf_(bf2f(rv[e])));
;       *(u16x8*)(P.ain + (long)r * D + c0 + hh * 8) = o;
;     }
	v_lshlrev_b32_e32 v28, 16, v2
	v_and_b32_e32 v29, 0xffff0000, v2
	v_mul_f32_e32 v2, 0xbfb8aa3b, v28
	v_exp_f32_e32 v2, v2
	v_pk_mul_f32 v[58:59], v[26:27], v[26:27]
	v_add_f32_e32 v2, 1.0, v2
	v_rcp_f32_e32 v74, v2
	v_mul_f32_e32 v2, 0xbfb8aa3b, v29
	v_exp_f32_e32 v2, v2
	s_nop 0
	v_add_f32_e32 v2, 1.0, v2
	v_rcp_f32_e32 v75, v2
	s_nop 0
	v_pk_mul_f32 v[28:29], v[74:75], v[28:29]
	v_and_b32_e32 v75, 0xffff0000, v15
	v_lshlrev_b32_e32 v74, 16, v15
	v_and_b32_e32 v15, 0xffff0000, v11
	v_and_b32_e32 v11, 0xffff0000, v7
	v_pk_add_f32 v[6:7], v[14:15], v[10:11]
	v_and_b32_e32 v15, 0xffff0000, v3
	v_lshlrev_b32_e32 v14, 16, v3
	v_mul_f32_e32 v2, 0xbfb8aa3b, v14
	v_mul_f32_e32 v3, 0xbfb8aa3b, v15
	v_exp_f32_e32 v2, v2
	v_exp_f32_e32 v3, v3
	v_pk_add_f32 v[10:11], v[6:7], v[74:75]
	v_add_f32_e32 v2, 1.0, v2
	v_add_f32_e32 v3, 1.0, v3
	v_rcp_f32_e32 v2, v2
	v_rcp_f32_e32 v3, v3
	v_pk_mul_f32 v[6:7], v[10:11], v[10:11]
	v_pk_mul_f32 v[2:3], v[2:3], v[14:15]
	v_and_b32_e32 v15, 0xffff0000, v16
	v_lshlrev_b32_e32 v14, 16, v16
	v_pk_add_f32 v[12:13], v[8:9], v[14:15]
	v_add_f32_e32 v14, v60, v61
	v_add_f32_e32 v14, v64, v14
	v_add_f32_e32 v14, v65, v14
	v_add_f32_e32 v14, v68, v14
	v_add_f32_e32 v14, v69, v14
	v_add_f32_e32 v14, v72, v14
	v_add_f32_e32 v14, v73, v14
	v_add_f32_e32 v14, v58, v14
	v_add_f32_e32 v14, v59, v14
	v_add_f32_e32 v6, v6, v14
	v_pk_mul_f32 v[8:9], v[12:13], v[12:13]
	v_add_f32_e32 v6, v7, v6
	v_add_f32_e32 v6, v8, v6
	v_add_f32_e32 v6, v9, v6
	v_add_f32_e32 v6, v32, v6
	v_add_f32_e32 v6, v33, v6
	ds_bpermute_b32 v7, v37, v6
	s_waitcnt lgkmcnt(0)
	v_add_f32_e32 v6, v6, v7
	ds_bpermute_b32 v7, v38, v6
	s_waitcnt lgkmcnt(0)
	v_add_f32_e32 v6, v6, v7
	ds_bpermute_b32 v7, v39, v6
	s_waitcnt lgkmcnt(0)
	v_add_f32_e32 v6, v6, v7
	ds_bpermute_b32 v7, v40, v6
	s_waitcnt lgkmcnt(0)
	v_add_f32_e32 v6, v6, v7
	v_fmamk_f32 v6, v6, 0x3b800000, v183
	v_cmp_gt_f32_e32 vcc, s9, v6
	v_mul_f32_e32 v7, 0x4b800000, v6
	s_nop 0
	v_cndmask_b32_e32 v6, v6, v7, vcc
	v_rsq_f32_e32 v6, v6
	s_nop 0
	v_mul_f32_e32 v7, 0x45800000, v6
	v_cndmask_b32_e32 v14, v6, v7, vcc
	v_pk_mul_f32 v[6:7], v[34:35], v[14:15] op_sel_hi:[1,0]
	v_pk_mul_f32 v[8:9], v[42:43], v[14:15] op_sel_hi:[1,0]
	v_pk_mul_f32 v[6:7], v[54:55], v[6:7]
	v_pk_mul_f32 v[8:9], v[56:57], v[8:9]
	v_pk_mul_f32 v[6:7], v[62:63], v[6:7]
	v_pk_mul_f32 v[8:9], v[46:47], v[8:9]
	v_cvt_pk_bf16_f32 v6, v6, v7
	v_cvt_pk_bf16_f32 v7, v8, v9
	v_pk_mul_f32 v[8:9], v[66:67], v[14:15] op_sel_hi:[1,0]
	v_pk_mul_f32 v[16:17], v[44:45], v[14:15] op_sel_hi:[1,0]
	v_pk_mul_f32 v[8:9], v[50:51], v[8:9]
	v_pk_mul_f32 v[16:17], v[52:53], v[16:17]
	v_pk_mul_f32 v[8:9], v[70:71], v[8:9]
	v_pk_mul_f32 v[16:17], v[48:49], v[16:17]
	v_cvt_pk_bf16_f32 v8, v8, v9
	v_cvt_pk_bf16_f32 v9, v16, v17
	v_add_co_u32_e32 v16, vcc, s16, v30
	v_pk_mul_f32 v[26:27], v[26:27], v[14:15] op_sel_hi:[1,0]
	s_nop 0
	v_addc_co_u32_e32 v17, vcc, 0, v31, vcc
	global_store_dwordx4 v[16:17], v[6:9], off offset:2048
	s_nop 1
	v_mov_b64_e32 v[6:7], v[212:213]
	v_mov_b64_e32 v[8:9], v[214:215]
	s_nop 0
	v_mov_b64_e32 v[30:31], v[216:217]
	v_mov_b64_e32 v[32:33], v[218:219]
	v_pk_mul_f32 v[10:11], v[10:11], v[14:15] op_sel_hi:[1,0]
	v_pk_mul_f32 v[12:13], v[12:13], v[14:15] op_sel_hi:[1,0]
	v_cmp_le_i32_e32 vcc, s93, v36
	s_or_b64 s[6:7], vcc, s[6:7]
	s_nop 0
	v_pk_mul_f32 v[6:7], v[6:7], v[12:13]
	v_pk_mul_f32 v[26:27], v[30:31], v[26:27]
	v_pk_mul_f32 v[10:11], v[32:33], v[10:11]
	v_pk_mul_f32 v[26:27], v[28:29], v[26:27]
	v_pk_mul_f32 v[2:3], v[2:3], v[10:11]
	v_cvt_pk_bf16_f32 v26, v26, v27
	v_cvt_pk_bf16_f32 v27, v2, v3
	v_lshlrev_b32_e32 v2, 16, v4
	v_and_b32_e32 v3, 0xffff0000, v4
	v_mul_f32_e32 v4, 0xbfb8aa3b, v2
	v_exp_f32_e32 v4, v4
	s_nop 0
	v_add_f32_e32 v4, 1.0, v4
	v_rcp_f32_e32 v10, v4
	v_mul_f32_e32 v4, 0xbfb8aa3b, v3
	v_exp_f32_e32 v4, v4
	s_nop 0
	v_add_f32_e32 v4, 1.0, v4
	v_rcp_f32_e32 v11, v4
	s_nop 0
	v_pk_mul_f32 v[2:3], v[10:11], v[2:3]
	s_nop 0
	v_pk_mul_f32 v[2:3], v[2:3], v[6:7]
	v_pk_mul_f32 v[6:7], v[24:25], v[14:15] op_sel_hi:[1,0]
	v_cvt_pk_bf16_f32 v28, v2, v3
	v_and_b32_e32 v3, 0xffff0000, v5
	v_lshlrev_b32_e32 v2, 16, v5
	v_mul_f32_e32 v4, 0xbfb8aa3b, v2
	v_mul_f32_e32 v5, 0xbfb8aa3b, v3
	v_exp_f32_e32 v4, v4
	v_exp_f32_e32 v5, v5
	v_pk_mul_f32 v[6:7], v[8:9], v[6:7]
	v_add_f32_e32 v4, 1.0, v4
	v_add_f32_e32 v5, 1.0, v5
	v_rcp_f32_e32 v4, v4
	v_rcp_f32_e32 v5, v5
	s_nop 0
	v_pk_mul_f32 v[2:3], v[4:5], v[2:3]
	s_nop 0
	v_pk_mul_f32 v[2:3], v[2:3], v[6:7]
	s_nop 0
	v_cvt_pk_bf16_f32 v29, v2, v3
	global_store_dwordx4 v[16:17], v[26:29], off offset:2064
	s_andn2_b64 exec, exec, s[6:7]
	s_cbranch_execnz .LBB0_155

; __device__ __forceinline__ void phase_glay_pool(const Params& P, char* shm, int grp, int l, int bid, int nb) {
;   const int gtok0 = P.gtok0, tg = P.tg;
;   const int ngla = grp == 0 ? 64 + 4 * 32 : 4 * 32;
;   const int npool = tg / 128;
;   for (int u = bid; u < ngla; u += nb) {
;     if (grp == 0 && u < 64) {
.LBB0_157:
	s_andn2_b64 vcc, exec, s[4:5]
	s_cbranch_vccnz .LBB0_303
	v_readlane_b32 s4, v248, 2
	s_add_i32 s4, s4, 31
	s_cmpk_lt_u32 s4, 0x41
	s_cselect_b64 s[14:15], -1, 0
	s_and_b64 s[4:5], s[14:15], exec
	s_movk_i32 s4, 0xc0
	s_cselect_b32 s29, s4, 0x80
	s_cmp_ge_i32 s44, s29
	s_cselect_b64 s[16:17], -1, 0
	s_and_b64 vcc, exec, s[16:17]
	s_cbranch_vccnz .LBB0_242
	s_and_b64 s[4:5], s[14:15], exec
	s_cselect_b32 s30, 0x4000, 0
	s_mov_b32 s31, s44
	s_branch .LBB0_162
	s_nop 0
	s_nop 0
	s_nop 0
	s_nop 0
	s_nop 0
	s_nop 0
	s_nop 0
	s_nop 0
	s_nop 0
	s_nop 0
	s_nop 0
	s_nop 0
	s_nop 0
	s_nop 0
	s_nop 0
	s_nop 0
	s_nop 0
	s_nop 0
	s_nop 0
	s_nop 0
	s_nop 0
	s_nop 0
	s_nop 0
	s_nop 0
	s_nop 0
	s_nop 0
	s_nop 0
	s_nop 0
	s_nop 0
	s_nop 0
	s_nop 0
	s_nop 0
	s_nop 0
	s_nop 0
	s_nop 0
	s_nop 0
	s_nop 0
	s_nop 0
	s_nop 0
	s_nop 0
	s_nop 0
	s_nop 0
	s_nop 0
	s_nop 0
	s_nop 0
	s_nop 0
	s_nop 0
	s_nop 0
	s_nop 0
	s_nop 0
	s_nop 0
